# G1 step 3: causal (tril) mask of the intra-chunk scores rewritten as one compare+select per element (the compiler copied the whole 16-register vector back and forth per element: ~390 v_mov_b64 and 43
# speedup vs baseline: 1.0066x; 1.0066x over previous
.LBB0_1112:
	v_lshlrev_b32_e32 v127, 2, v158
	s_nop 7
	s_nop 7
	s_and_b64 vcc, exec, s[0:1]
	s_cbranch_vccz .Ltril_ib1
	v_or_b32_e32 v99, 1, v127
	v_cmp_gt_u32_e64 s[8:9], v127, v156
	v_cmp_gt_u32_e64 s[18:19], v99, v156
	s_nop 0
	v_cndmask_b32_e64 v66, v66, 0, s[8:9]
	v_cndmask_b32_e64 v67, v67, 0, s[18:19]
	v_or_b32_e32 v98, 2, v127
	v_or_b32_e32 v99, 3, v127
	v_cmp_gt_u32_e64 s[8:9], v98, v156
	v_cmp_gt_u32_e64 s[18:19], v99, v156
	s_nop 0
	v_cndmask_b32_e64 v68, v68, 0, s[8:9]
	v_cndmask_b32_e64 v69, v69, 0, s[18:19]
	v_or_b32_e32 v98, 8, v127
	v_or_b32_e32 v99, 9, v127
	v_cmp_gt_u32_e64 s[8:9], v98, v156
	v_cmp_gt_u32_e64 s[18:19], v99, v156
	s_nop 0
	v_cndmask_b32_e64 v70, v70, 0, s[8:9]
	v_cndmask_b32_e64 v71, v71, 0, s[18:19]
	v_or_b32_e32 v98, 10, v127
	v_or_b32_e32 v99, 11, v127
	v_cmp_gt_u32_e64 s[8:9], v98, v156
	v_cmp_gt_u32_e64 s[18:19], v99, v156
	s_nop 0
	v_cndmask_b32_e64 v72, v72, 0, s[8:9]
	v_cndmask_b32_e64 v73, v73, 0, s[18:19]
	v_or_b32_e32 v98, 16, v127
	v_or_b32_e32 v99, 17, v127
	v_cmp_gt_u32_e64 s[8:9], v98, v156
	v_cmp_gt_u32_e64 s[18:19], v99, v156
	s_nop 0
	v_cndmask_b32_e64 v74, v74, 0, s[8:9]
	v_cndmask_b32_e64 v75, v75, 0, s[18:19]
	v_or_b32_e32 v98, 18, v127
	v_or_b32_e32 v99, 19, v127
	v_cmp_gt_u32_e64 s[8:9], v98, v156
	v_cmp_gt_u32_e64 s[18:19], v99, v156
	s_nop 0
	v_cndmask_b32_e64 v76, v76, 0, s[8:9]
	v_cndmask_b32_e64 v77, v77, 0, s[18:19]
	v_or_b32_e32 v98, 24, v127
	v_or_b32_e32 v99, 25, v127
	v_cmp_gt_u32_e64 s[8:9], v98, v156
	v_cmp_gt_u32_e64 s[18:19], v99, v156
	s_nop 0
	v_cndmask_b32_e64 v78, v78, 0, s[8:9]
	v_cndmask_b32_e64 v79, v79, 0, s[18:19]
	v_or_b32_e32 v98, 26, v127
	v_or_b32_e32 v99, 27, v127
	v_cmp_gt_u32_e64 s[8:9], v98, v156
	v_cmp_gt_u32_e64 s[18:19], v99, v156
	s_nop 0
	v_cndmask_b32_e64 v80, v80, 0, s[8:9]
	v_cndmask_b32_e64 v81, v81, 0, s[18:19]
	s_branch .LBB0_1255
.Ltril_ib1:
	v_or_b32_e32 v99, 1, v127
	v_cmp_gt_u32_e64 s[8:9], v127, v156
	v_cmp_gt_u32_e64 s[18:19], v99, v156
	s_nop 0
	v_cndmask_b32_e64 v82, v82, 0, s[8:9]
	v_cndmask_b32_e64 v83, v83, 0, s[18:19]
	v_or_b32_e32 v98, 2, v127
	v_or_b32_e32 v99, 3, v127
	v_cmp_gt_u32_e64 s[8:9], v98, v156
	v_cmp_gt_u32_e64 s[18:19], v99, v156
	s_nop 0
	v_cndmask_b32_e64 v84, v84, 0, s[8:9]
	v_cndmask_b32_e64 v85, v85, 0, s[18:19]
	v_or_b32_e32 v98, 8, v127
	v_or_b32_e32 v99, 9, v127
	v_cmp_gt_u32_e64 s[8:9], v98, v156
	v_cmp_gt_u32_e64 s[18:19], v99, v156
	s_nop 0
	v_cndmask_b32_e64 v86, v86, 0, s[8:9]
	v_cndmask_b32_e64 v87, v87, 0, s[18:19]
	v_or_b32_e32 v98, 10, v127
	v_or_b32_e32 v99, 11, v127
	v_cmp_gt_u32_e64 s[8:9], v98, v156
	v_cmp_gt_u32_e64 s[18:19], v99, v156
	s_nop 0
	v_cndmask_b32_e64 v88, v88, 0, s[8:9]
	v_cndmask_b32_e64 v89, v89, 0, s[18:19]
	v_or_b32_e32 v98, 16, v127
	v_or_b32_e32 v99, 17, v127
	v_cmp_gt_u32_e64 s[8:9], v98, v156
	v_cmp_gt_u32_e64 s[18:19], v99, v156
	s_nop 0
	v_cndmask_b32_e64 v90, v90, 0, s[8:9]
	v_cndmask_b32_e64 v91, v91, 0, s[18:19]
	v_or_b32_e32 v98, 18, v127
	v_or_b32_e32 v99, 19, v127
	v_cmp_gt_u32_e64 s[8:9], v98, v156
	v_cmp_gt_u32_e64 s[18:19], v99, v156
	s_nop 0
	v_cndmask_b32_e64 v92, v92, 0, s[8:9]
	v_cndmask_b32_e64 v93, v93, 0, s[18:19]
	v_or_b32_e32 v98, 24, v127
	v_or_b32_e32 v99, 25, v127
	v_cmp_gt_u32_e64 s[8:9], v98, v156
	v_cmp_gt_u32_e64 s[18:19], v99, v156
	s_nop 0
	v_cndmask_b32_e64 v94, v94, 0, s[8:9]
	v_cndmask_b32_e64 v95, v95, 0, s[18:19]
	v_or_b32_e32 v98, 26, v127
	v_or_b32_e32 v99, 27, v127
	v_cmp_gt_u32_e64 s[8:9], v98, v156
	v_cmp_gt_u32_e64 s[18:19], v99, v156
	s_nop 0
	v_cndmask_b32_e64 v96, v96, 0, s[8:9]
	v_cndmask_b32_e64 v97, v97, 0, s[18:19]
